# phase skew: half of the 8-workgroup groups in every XCD start the merged GEMM ~7us later, so HBM-bound epilogues of one half overlap MFMA-bound loops of the other
# speedup vs baseline: 1.0070x; 1.0070x over previous
; __global__ void __launch_bounds__(NTHREADS, 2) skel_fwd(Args args) {
;     ...
;     if (IN(4)) {
;     ...
;         { pg8::SchedP3m S{F.G, (int)blockIdx.x, (const char*)F.SBQ, (const char*)F.Wbr_t};
;           pg8::EpiMergedR E{F.G0, F.G2, F.MRG};
;           pg8::gemm_phase<pg8::EpiMergedR, pg8::SchedP3m, true, true, 3>(F.lds, DH, S, E); }
.LBB0_561:
	s_bfe_u32 s2, s90, 0x10003
	s_cmp_eq_u32 s2, 0
	s_cbranch_scc1 .Lskew_skip
	s_sleep 127
	s_sleep 127
